# final-phase and init-phase output stores device-scope
# speedup vs baseline: 1.0036x; 1.0036x over previous
; __device__ __forceinline__ void store8bf(bf16_t* p, f32x4 v0, f32x4 v1) { u32x4 w; w.x = cvt_pk_bf16(v0[0], v0[1]); w.y = cvt_pk_bf16(v0[2], v0[3]); w.z = cvt_pk_bf16(v1[0], v1[1]); w.w = cvt_pk_bf16(v1[2], v1[3]); *(u32x4*)p = w; }
; __device__ __forceinline__ void init_phase(const float* x, const float* meta, const float* g, bf16_t* HN) {
;     ...
;   for (int row = gw; row < NREAL + 64; row += 2 * nw) {
;     const int row2 = row + nw < NREAL + 64 ? row + nw : row;
;     const float* p = (row < NREAL ? x + (size_t)row * DM : meta + (size_t)((row - NREAL) & 15) * DM) + lane * 8;
;     const float* p2 = (row2 < NREAL ? x + (size_t)row2 * DM : meta + (size_t)((row2 - NREAL) & 15) * DM) + lane * 8;
;     f32x4 v[4], u[4]; float ss = 0.f, ss2 = 0.f;
; #pragma unroll
;     for (int i = 0; i < 4; ++i) { v[i] = *(const f32x4*)(p + 512 * (i >> 1) + 4 * (i & 1)); u[i] = *(const f32x4*)(p2 + 512 * (i >> 1) + 4 * (i & 1)); }
; #pragma unroll
;     for (int i = 0; i < 4; ++i) { ss += v[i][0] * v[i][0] + v[i][1] * v[i][1] + v[i][2] * v[i][2] + v[i][3] * v[i][3]; ss2 += u[i][0] * u[i][0] + u[i][1] * u[i][1] + u[i][2] * u[i][2] + u[i][3] * u[i][3]; }
;     ss = wave_sum(ss); ss2 = wave_sum(ss2); const float rs = rsqrtf(ss * (1.0f / 1024.0f) + 1e-6f), rs2 = rsqrtf(ss2 * (1.0f / 1024.0f) + 1e-6f);
;     bf16_t* q = HN + (size_t)row * DM + lane * 8; bf16_t* q2 = HN + (size_t)row2 * DM + lane * 8;
; #pragma unroll
;     for (int i = 0; i < 2; ++i) { store8bf(q + 512 * i, v[2 * i] * rs * gv[2 * i], v[2 * i + 1] * rs * gv[2 * i + 1]); store8bf(q2 + 512 * i, u[2 * i] * rs2 * gv[2 * i], u[2 * i + 1] * rs2 * gv[2 * i + 1]); }
.LBB0_199:
	s_or_b64 exec, exec, s[0:1]
	v_lshl_add_u64 v[18:19], v[18:19], 0, v[42:43]
	global_load_dwordx4 v[54:57], v[18:19], off
	global_load_dwordx4 v[58:61], v[18:19], off offset:16
	v_lshl_add_u64 v[30:31], v[20:21], 0, v[42:43]
	global_load_dwordx4 v[34:37], v[30:31], off
	global_load_dwordx4 v[26:29], v[30:31], off offset:16
	global_load_dwordx4 v[22:25], v[18:19], off offset:2048
	s_nop 0
	global_load_dwordx4 v[18:21], v[18:19], off offset:2064
	s_nop 0
	global_load_dwordx4 v[38:41], v[30:31], off offset:2048
	s_nop 0
	global_load_dwordx4 v[30:33], v[30:31], off offset:2064
	v_lshlrev_b64 v[48:49], 11, v[48:49]
	v_lshlrev_b64 v[50:51], 11, v[50:51]
	v_lshl_add_u64 v[48:49], v[44:45], 0, v[48:49]
	v_lshl_add_u64 v[50:51], v[44:45], 0, v[50:51]
	v_add_u32_e32 v52, s8, v52
	s_waitcnt vmcnt(5)
	v_mov_b32_e32 v68, v35
	s_waitcnt vmcnt(4)
	v_mov_b32_e32 v69, v27
	v_mov_b32_e32 v64, v55
	v_mov_b32_e32 v65, v59
	v_mov_b32_e32 v62, v54
	v_mov_b32_e32 v63, v58
	v_mov_b32_e32 v66, v34
	v_mov_b32_e32 v67, v26
	s_waitcnt vmcnt(3)
	v_mov_b32_e32 v72, v23
	s_waitcnt vmcnt(2)
	v_mov_b32_e32 v73, v19
	s_waitcnt vmcnt(1)
	v_mov_b32_e32 v76, v39
	s_waitcnt vmcnt(0)
	v_mov_b32_e32 v77, v31
	v_pk_mul_f32 v[64:65], v[64:65], v[64:65]
	v_pk_mul_f32 v[68:69], v[68:69], v[68:69]
	v_mov_b32_e32 v70, v22
	v_mov_b32_e32 v71, v18
	v_mov_b32_e32 v74, v38
	v_mov_b32_e32 v75, v30
	v_mov_b32_e32 v78, v56
	v_mov_b32_e32 v79, v60
	v_mov_b32_e32 v80, v36
	v_mov_b32_e32 v81, v28
	v_pk_mul_f32 v[72:73], v[72:73], v[72:73]
	v_pk_mul_f32 v[76:77], v[76:77], v[76:77]
	v_pk_fma_f32 v[62:63], v[62:63], v[62:63], v[64:65]
	v_pk_fma_f32 v[64:65], v[66:67], v[66:67], v[68:69]
	v_mov_b32_e32 v82, v24
	v_mov_b32_e32 v83, v20
	v_mov_b32_e32 v84, v40
	v_mov_b32_e32 v85, v32
	v_mov_b32_e32 v86, v57
	v_mov_b32_e32 v87, v61
	v_mov_b32_e32 v88, v37
	v_mov_b32_e32 v89, v29
	v_pk_fma_f32 v[66:67], v[70:71], v[70:71], v[72:73]
	v_pk_fma_f32 v[68:69], v[74:75], v[74:75], v[76:77]
	v_pk_fma_f32 v[62:63], v[78:79], v[78:79], v[62:63]
	v_pk_fma_f32 v[64:65], v[80:81], v[80:81], v[64:65]
	v_mov_b32_e32 v90, v25
	v_mov_b32_e32 v91, v21
	v_mov_b32_e32 v92, v41
	v_mov_b32_e32 v93, v33
	v_pk_fma_f32 v[66:67], v[82:83], v[82:83], v[66:67]
	v_pk_fma_f32 v[68:69], v[84:85], v[84:85], v[68:69]
	v_pk_fma_f32 v[62:63], v[86:87], v[86:87], v[62:63]
	v_pk_fma_f32 v[64:65], v[88:89], v[88:89], v[64:65]
	v_pk_fma_f32 v[66:67], v[90:91], v[90:91], v[66:67]
	v_pk_fma_f32 v[68:69], v[92:93], v[92:93], v[68:69]
	v_mov_b32_e32 v70, v64
	v_mov_b32_e32 v71, v62
	v_mov_b32_e32 v62, v65
	v_mov_b32_e32 v64, v68
	v_mov_b32_e32 v65, v66
	v_pk_add_f32 v[62:63], v[70:71], v[62:63]
	v_mov_b32_e32 v66, v69
	v_pk_add_f32 v[62:63], v[62:63], v[64:65]
	s_nop 0
	v_pk_add_f32 v[62:63], v[62:63], v[66:67]
	ds_swizzle_b32 v65, v63 offset:swizzle(SWAP,16)
	ds_swizzle_b32 v64, v62 offset:swizzle(SWAP,16)
	v_mov_b32_e32 v66, v1
	v_mov_b32_e32 v67, v1
	s_waitcnt lgkmcnt(0)
	v_pk_add_f32 v[62:63], v[62:63], v[64:65]
	ds_swizzle_b32 v65, v63 offset:swizzle(SWAP,8)
	ds_swizzle_b32 v64, v62 offset:swizzle(SWAP,8)
	v_lshlrev_b32_e32 v66, 2, v66
	v_lshlrev_b32_e32 v67, 2, v67
	v_xor_b32_e32 v66, 0x80, v66
	v_xor_b32_e32 v67, 0x80, v67
	s_waitcnt lgkmcnt(0)
	v_pk_add_f32 v[62:63], v[62:63], v[64:65]
	ds_swizzle_b32 v65, v63 offset:swizzle(SWAP,4)
	ds_swizzle_b32 v64, v62 offset:swizzle(SWAP,4)
	s_waitcnt lgkmcnt(0)
	v_pk_add_f32 v[62:63], v[62:63], v[64:65]
	ds_swizzle_b32 v65, v63 offset:swizzle(SWAP,2)
	ds_swizzle_b32 v64, v62 offset:swizzle(SWAP,2)
	s_waitcnt lgkmcnt(0)
	v_pk_add_f32 v[62:63], v[62:63], v[64:65]
	ds_swizzle_b32 v65, v63 offset:swizzle(SWAP,1)
	ds_swizzle_b32 v64, v62 offset:swizzle(SWAP,1)
	s_waitcnt lgkmcnt(0)
	v_pk_add_f32 v[62:63], v[62:63], v[64:65]
	ds_bpermute_b32 v65, v66, v63
	ds_bpermute_b32 v64, v67, v62
	s_waitcnt lgkmcnt(0)
	v_pk_add_f32 v[62:63], v[62:63], v[64:65]
	s_nop 0
	v_pk_fma_f32 v[62:63], v[62:63], s[6:7], v[46:47] op_sel_hi:[1,0,0]
	s_nop 0
	v_mul_f32_e32 v64, 0x4b800000, v63
	v_cmp_gt_f32_e32 vcc, s10, v63
	v_mul_f32_e32 v65, 0x4b800000, v62
	v_cmp_gt_f32_e64 s[0:1], s10, v62
	v_cndmask_b32_e32 v63, v63, v64, vcc
	v_rsq_f32_e32 v63, v63
	v_cndmask_b32_e64 v62, v62, v65, s[0:1]
	v_rsq_f32_e32 v64, v62
	v_mul_f32_e32 v62, 0x45800000, v63
	v_cndmask_b32_e32 v62, v63, v62, vcc
	v_mul_f32_e32 v65, 0x45800000, v64
	v_cndmask_b32_e64 v64, v64, v65, s[0:1]
	v_pk_mul_f32 v[54:55], v[54:55], v[62:63] op_sel_hi:[1,0]
	v_pk_mul_f32 v[56:57], v[56:57], v[62:63] op_sel_hi:[1,0]
	v_pk_mul_f32 v[58:59], v[58:59], v[62:63] op_sel_hi:[1,0]
	v_pk_mul_f32 v[60:61], v[60:61], v[62:63] op_sel_hi:[1,0]
	v_pk_mul_f32 v[34:35], v[34:35], v[64:65] op_sel_hi:[1,0]
	v_pk_mul_f32 v[36:37], v[36:37], v[64:65] op_sel_hi:[1,0]
	v_pk_mul_f32 v[26:27], v[26:27], v[64:65] op_sel_hi:[1,0]
	v_pk_mul_f32 v[28:29], v[28:29], v[64:65] op_sel_hi:[1,0]
	v_pk_mul_f32 v[66:67], v[22:23], v[62:63] op_sel_hi:[1,0]
	v_pk_mul_f32 v[22:23], v[24:25], v[62:63] op_sel_hi:[1,0]
	v_pk_mul_f32 v[24:25], v[8:9], v[56:57]
	v_pk_mul_f32 v[54:55], v[6:7], v[54:55]
	v_pk_mul_f32 v[56:57], v[4:5], v[60:61]
	v_pk_mul_f32 v[58:59], v[2:3], v[58:59]
	v_pk_mul_f32 v[36:37], v[8:9], v[36:37]
	v_pk_mul_f32 v[34:35], v[6:7], v[34:35]
	v_pk_mul_f32 v[60:61], v[4:5], v[28:29]
	v_pk_mul_f32 v[28:29], v[2:3], v[26:27]
	v_pk_mul_f32 v[68:69], v[16:17], v[22:23]
	v_cvt_pk_bf16_f32 v22, v54, v55
	v_cvt_pk_bf16_f32 v23, v24, v25
	v_cvt_pk_bf16_f32 v24, v58, v59
	v_cvt_pk_bf16_f32 v25, v56, v57
	v_pk_mul_f32 v[18:19], v[18:19], v[62:63] op_sel_hi:[1,0]
	v_pk_mul_f32 v[20:21], v[20:21], v[62:63] op_sel_hi:[1,0]
	v_cvt_pk_bf16_f32 v26, v34, v35
	v_cvt_pk_bf16_f32 v27, v36, v37
	v_cvt_pk_bf16_f32 v28, v28, v29
	v_cvt_pk_bf16_f32 v29, v60, v61
	global_store_dwordx4 v[48:49], v[22:25], off sc1
	global_store_dwordx4 v[50:51], v[26:29], off sc1
	s_nop 0
	v_pk_mul_f32 v[22:23], v[14:15], v[66:67]
	v_pk_mul_f32 v[24:25], v[12:13], v[20:21]
	v_pk_mul_f32 v[20:21], v[10:11], v[18:19]
	v_cvt_pk_bf16_f32 v18, v22, v23
	v_cvt_pk_bf16_f32 v19, v68, v69
	v_cvt_pk_bf16_f32 v20, v20, v21
	v_cvt_pk_bf16_f32 v21, v24, v25
	global_store_dwordx4 v[48:49], v[18:21], off offset:1024 sc1
	v_pk_mul_f32 v[22:23], v[30:31], v[64:65] op_sel_hi:[1,0]
	v_pk_mul_f32 v[24:25], v[32:33], v[64:65] op_sel_hi:[1,0]
	v_pk_mul_f32 v[18:19], v[38:39], v[64:65] op_sel_hi:[1,0]
	v_pk_mul_f32 v[20:21], v[40:41], v[64:65] op_sel_hi:[1,0]
	v_add_u32_e32 v48, s28, v53
	v_pk_mul_f32 v[20:21], v[16:17], v[20:21]
	v_pk_mul_f32 v[18:19], v[14:15], v[18:19]
	v_pk_mul_f32 v[24:25], v[12:13], v[24:25]
	v_pk_mul_f32 v[22:23], v[10:11], v[22:23]
	v_cmp_lt_i32_e32 vcc, s11, v48
	v_cvt_pk_bf16_f32 v18, v18, v19
	v_cvt_pk_bf16_f32 v19, v20, v21
	v_cvt_pk_bf16_f32 v20, v22, v23
	v_cvt_pk_bf16_f32 v21, v24, v25
	s_or_b64 s[4:5], vcc, s[4:5]
	global_store_dwordx4 v[50:51], v[18:21], off offset:1024 sc1
	s_andn2_b64 exec, exec, s[4:5]
	s_cbranch_execz .LBB0_208

; __device__ __forceinline__ void final_phase(const float* H, const float* g, float* out) {
;     ...
;   for (int row = gw; row < NREAL; row += 2 * nw) {
;     const int row2 = row + nw < NREAL ? row + nw : row;
;     const float* p = H + (size_t)row * DM + lane * 4; const float* p2 = H + (size_t)row2 * DM + lane * 4; f32x4 v[4], u[4]; float ss = 0.f, ss2 = 0.f;
; #pragma unroll
;     for (int i = 0; i < 4; ++i) { v[i] = *(const f32x4*)(p + 256 * i); u[i] = *(const f32x4*)(p2 + 256 * i); }
; #pragma unroll
;     for (int i = 0; i < 4; ++i) { ss += v[i][0] * v[i][0] + v[i][1] * v[i][1] + v[i][2] * v[i][2] + v[i][3] * v[i][3]; ss2 += u[i][0] * u[i][0] + u[i][1] * u[i][1] + u[i][2] * u[i][2] + u[i][3] * u[i][3]; }
;     ss = wave_sum(ss); ss2 = wave_sum(ss2); const float rs = rsqrtf(ss * (1.0f / 1024.0f) + 1e-6f), rs2 = rsqrtf(ss2 * (1.0f / 1024.0f) + 1e-6f);
.LBB0_1577:
	v_readfirstlane_b32 s8, v22
	s_nop 3
	s_lshl_b32 s10, s16, 1
	s_add_i32 s11, s8, s16
	s_cmp_lt_i32 s11, s5
	s_cselect_b32 s11, s11, s8
	s_lshl_b32 s12, s8, 12
	s_lshl_b32 s13, s11, 12
	v_mov_b32_e32 v82, s12
	v_mov_b32_e32 v83, 0
	v_lshl_add_u64 v[84:85], v[16:17], 0, v[82:83]
	v_lshl_add_u64 v[56:57], v[18:19], 0, v[82:83]
	v_mov_b32_e32 v82, s13
	v_lshl_add_u64 v[86:87], v[16:17], 0, v[82:83]
	v_lshl_add_u64 v[60:61], v[18:19], 0, v[82:83]
	global_load_dwordx4 v[24:27], v[84:85], off
	global_load_dwordx4 v[28:31], v[84:85], off offset:1024
	global_load_dwordx4 v[32:35], v[84:85], off offset:2048
	global_load_dwordx4 v[36:39], v[84:85], off offset:3072
	global_load_dwordx4 v[40:43], v[86:87], off
	global_load_dwordx4 v[44:47], v[86:87], off offset:1024
	global_load_dwordx4 v[48:51], v[86:87], off offset:2048
	global_load_dwordx4 v[52:55], v[86:87], off offset:3072
	s_add_i32 s9, s8, s10
	s_cmp_lt_i32 s9, s5
	s_cbranch_scc0 .Lfn_lastA_first
	s_add_i32 s11, s9, s16
	s_cmp_lt_i32 s11, s5
	s_cselect_b32 s11, s11, s9
	s_lshl_b32 s12, s9, 12
	s_lshl_b32 s13, s11, 12
	v_mov_b32_e32 v82, s12
	v_mov_b32_e32 v83, 0
	v_lshl_add_u64 v[84:85], v[16:17], 0, v[82:83]
	v_lshl_add_u64 v[132:133], v[18:19], 0, v[82:83]
	v_mov_b32_e32 v82, s13
	v_lshl_add_u64 v[86:87], v[16:17], 0, v[82:83]
	v_lshl_add_u64 v[134:135], v[18:19], 0, v[82:83]
	global_load_dwordx4 v[100:103], v[84:85], off
	global_load_dwordx4 v[104:107], v[84:85], off offset:1024
	global_load_dwordx4 v[108:111], v[84:85], off offset:2048
	global_load_dwordx4 v[112:115], v[84:85], off offset:3072
	global_load_dwordx4 v[116:119], v[86:87], off
	global_load_dwordx4 v[120:123], v[86:87], off offset:1024
	global_load_dwordx4 v[124:127], v[86:87], off offset:2048
	global_load_dwordx4 v[128:131], v[86:87], off offset:3072
	s_waitcnt vmcnt(8)
	v_lshlrev_b32_e32 v21, 2, v210
	v_xor_b32_e32 v21, 0x80, v21
	v_mov_b32_e32 v23, v21
	v_mov_b32_e32 v62, v25
	v_mov_b32_e32 v63, v29
	v_mov_b32_e32 v70, v33
	v_mov_b32_e32 v71, v37
	v_mov_b32_e32 v58, v24
	v_mov_b32_e32 v59, v28
	v_mov_b32_e32 v68, v32
	v_mov_b32_e32 v69, v36
	v_pk_mul_f32 v[62:63], v[62:63], v[62:63]
	v_pk_mul_f32 v[70:71], v[70:71], v[70:71]
	v_mov_b32_e32 v64, v26
	v_mov_b32_e32 v65, v30
	v_pk_fma_f32 v[58:59], v[58:59], v[58:59], v[62:63]
	v_pk_fma_f32 v[62:63], v[68:69], v[68:69], v[70:71]
	v_mov_b32_e32 v70, v41
	v_mov_b32_e32 v71, v45
	v_mov_b32_e32 v68, v40
	v_mov_b32_e32 v69, v44
	v_mov_b32_e32 v80, v49
	v_mov_b32_e32 v81, v53
	v_pk_fma_f32 v[58:59], v[64:65], v[64:65], v[58:59]
	v_pk_mul_f32 v[64:65], v[70:71], v[70:71]
	v_mov_b32_e32 v66, v27
	v_mov_b32_e32 v67, v31
	v_mov_b32_e32 v76, v42
	v_mov_b32_e32 v77, v46
	v_mov_b32_e32 v78, v48
	v_mov_b32_e32 v79, v52
	v_pk_mul_f32 v[70:71], v[80:81], v[80:81]
	v_pk_fma_f32 v[64:65], v[68:69], v[68:69], v[64:65]
	v_mov_b32_e32 v72, v34
	v_mov_b32_e32 v73, v38
	v_mov_b32_e32 v82, v43
	v_mov_b32_e32 v83, v47
	v_mov_b32_e32 v84, v50
	v_mov_b32_e32 v85, v54
	v_pk_fma_f32 v[58:59], v[66:67], v[66:67], v[58:59]
	v_pk_fma_f32 v[66:67], v[78:79], v[78:79], v[70:71]
	v_pk_fma_f32 v[64:65], v[76:77], v[76:77], v[64:65]
	v_mov_b32_e32 v74, v35
	v_mov_b32_e32 v75, v39
	v_mov_b32_e32 v86, v51
	v_mov_b32_e32 v87, v55
	v_pk_fma_f32 v[62:63], v[72:73], v[72:73], v[62:63]
	v_pk_fma_f32 v[66:67], v[84:85], v[84:85], v[66:67]
	v_pk_fma_f32 v[64:65], v[82:83], v[82:83], v[64:65]
	v_pk_fma_f32 v[62:63], v[74:75], v[74:75], v[62:63]
	v_mov_b32_e32 v69, v58
	v_pk_fma_f32 v[66:67], v[86:87], v[86:87], v[66:67]
	v_mov_b32_e32 v68, v64
	v_mov_b32_e32 v58, v65
	v_mov_b32_e32 v71, v62
	v_mov_b32_e32 v70, v66
	v_pk_add_f32 v[58:59], v[68:69], v[58:59]
	v_mov_b32_e32 v62, v67
	v_pk_add_f32 v[58:59], v[58:59], v[70:71]
	s_nop 0
	v_pk_add_f32 v[58:59], v[58:59], v[62:63]
	ds_swizzle_b32 v63, v59 offset:swizzle(SWAP,16)
	ds_swizzle_b32 v62, v58 offset:swizzle(SWAP,16)
	s_waitcnt lgkmcnt(0)
	v_pk_add_f32 v[58:59], v[58:59], v[62:63]
	ds_swizzle_b32 v63, v59 offset:swizzle(SWAP,8)
	ds_swizzle_b32 v62, v58 offset:swizzle(SWAP,8)
	s_waitcnt lgkmcnt(0)
	v_pk_add_f32 v[58:59], v[58:59], v[62:63]
	ds_swizzle_b32 v63, v59 offset:swizzle(SWAP,4)
	ds_swizzle_b32 v62, v58 offset:swizzle(SWAP,4)
	s_waitcnt lgkmcnt(0)
	v_pk_add_f32 v[58:59], v[58:59], v[62:63]
	ds_swizzle_b32 v63, v59 offset:swizzle(SWAP,2)
	ds_swizzle_b32 v62, v58 offset:swizzle(SWAP,2)
	s_waitcnt lgkmcnt(0)
	v_pk_add_f32 v[58:59], v[58:59], v[62:63]
	ds_swizzle_b32 v63, v59 offset:swizzle(SWAP,1)
	ds_swizzle_b32 v62, v58 offset:swizzle(SWAP,1)
	s_waitcnt lgkmcnt(0)
	v_pk_add_f32 v[58:59], v[58:59], v[62:63]
	ds_bpermute_b32 v63, v21, v59
	ds_bpermute_b32 v62, v23, v58
	s_waitcnt lgkmcnt(0)
; __device__ __forceinline__ void final_phase(const float* H, const float* g, float* out) {
;     ...
;     const float* p = H + (size_t)row * DM + lane * 4; const float* p2 = H + (size_t)row2 * DM + lane * 4; f32x4 v[4], u[4]; float ss = 0.f, ss2 = 0.f;
; #pragma unroll
;     for (int i = 0; i < 4; ++i) { v[i] = *(const f32x4*)(p + 256 * i); u[i] = *(const f32x4*)(p2 + 256 * i); }
; #pragma unroll
;     for (int i = 0; i < 4; ++i) { ss += v[i][0] * v[i][0] + v[i][1] * v[i][1] + v[i][2] * v[i][2] + v[i][3] * v[i][3]; ss2 += u[i][0] * u[i][0] + u[i][1] * u[i][1] + u[i][2] * u[i][2] + u[i][3] * u[i][3]; }
;     ss = wave_sum(ss); ss2 = wave_sum(ss2); const float rs = rsqrtf(ss * (1.0f / 1024.0f) + 1e-6f), rs2 = rsqrtf(ss2 * (1.0f / 1024.0f) + 1e-6f);
;     float* q = out + (size_t)row * DM + lane * 4; float* q2 = out + (size_t)row2 * DM + lane * 4;
; #pragma unroll
;     for (int i = 0; i < 4; ++i) { *(f32x4*)(q + 256 * i) = v[i] * rs * gv[i]; *(f32x4*)(q2 + 256 * i) = u[i] * rs2 * gv[i]; }
	v_pk_add_f32 v[58:59], v[58:59], v[62:63]
	s_nop 0
	v_pk_fma_f32 v[58:59], v[58:59], s[4:5], v[20:21] op_sel_hi:[1,0,0]
	s_nop 0
	v_mul_f32_e32 v21, 0x4b800000, v59
	v_cmp_gt_f32_e64 s[0:1], s6, v59
	v_mul_f32_e32 v23, 0x4b800000, v58
	v_cmp_gt_f32_e32 vcc, s6, v58
	v_cndmask_b32_e64 v21, v59, v21, s[0:1]
	v_rsq_f32_e32 v21, v21
	v_cndmask_b32_e32 v23, v58, v23, vcc
	v_rsq_f32_e32 v23, v23
	v_mul_f32_e32 v58, 0x45800000, v21
	v_cndmask_b32_e64 v58, v21, v58, s[0:1]
	v_mul_f32_e32 v59, 0x45800000, v23
	v_cndmask_b32_e32 v62, v23, v59, vcc
	v_pk_mul_f32 v[24:25], v[24:25], v[58:59] op_sel_hi:[1,0]
	v_pk_mul_f32 v[26:27], v[26:27], v[58:59] op_sel_hi:[1,0]
	v_pk_mul_f32 v[40:41], v[40:41], v[62:63] op_sel_hi:[1,0]
	v_pk_mul_f32 v[42:43], v[42:43], v[62:63] op_sel_hi:[1,0]
	v_pk_mul_f32 v[64:65], v[28:29], v[58:59] op_sel_hi:[1,0]
	v_pk_mul_f32 v[66:67], v[30:31], v[58:59] op_sel_hi:[1,0]
	v_pk_mul_f32 v[44:45], v[44:45], v[62:63] op_sel_hi:[1,0]
	v_pk_mul_f32 v[46:47], v[46:47], v[62:63] op_sel_hi:[1,0]
	v_pk_mul_f32 v[68:69], v[32:33], v[58:59] op_sel_hi:[1,0]
	v_pk_mul_f32 v[70:71], v[34:35], v[58:59] op_sel_hi:[1,0]
	v_pk_mul_f32 v[48:49], v[48:49], v[62:63] op_sel_hi:[1,0]
	v_pk_mul_f32 v[50:51], v[50:51], v[62:63] op_sel_hi:[1,0]
	v_pk_mul_f32 v[72:73], v[36:37], v[58:59] op_sel_hi:[1,0]
	v_pk_mul_f32 v[58:59], v[38:39], v[58:59] op_sel_hi:[1,0]
	v_pk_mul_f32 v[52:53], v[52:53], v[62:63] op_sel_hi:[1,0]
	v_pk_mul_f32 v[54:55], v[54:55], v[62:63] op_sel_hi:[1,0]
	v_pk_mul_f32 v[26:27], v[2:3], v[26:27]
	v_pk_mul_f32 v[24:25], v[0:1], v[24:25]
	v_pk_mul_f32 v[30:31], v[2:3], v[42:43]
	v_pk_mul_f32 v[28:29], v[0:1], v[40:41]
	v_pk_mul_f32 v[34:35], v[6:7], v[66:67]
	v_pk_mul_f32 v[32:33], v[4:5], v[64:65]
	v_pk_mul_f32 v[38:39], v[6:7], v[46:47]
	v_pk_mul_f32 v[36:37], v[4:5], v[44:45]
	v_pk_mul_f32 v[42:43], v[10:11], v[70:71]
	v_pk_mul_f32 v[40:41], v[8:9], v[68:69]
	v_pk_mul_f32 v[46:47], v[10:11], v[50:51]
	v_pk_mul_f32 v[44:45], v[8:9], v[48:49]
	v_pk_mul_f32 v[50:51], v[14:15], v[58:59]
	v_pk_mul_f32 v[48:49], v[12:13], v[72:73]
	v_pk_mul_f32 v[54:55], v[14:15], v[54:55]
	v_pk_mul_f32 v[52:53], v[12:13], v[52:53]
	global_store_dwordx4 v[56:57], v[24:27], off sc1
	global_store_dwordx4 v[60:61], v[28:31], off sc1
	global_store_dwordx4 v[56:57], v[32:35], off offset:1024 sc1
	global_store_dwordx4 v[60:61], v[36:39], off offset:1024 sc1
	global_store_dwordx4 v[56:57], v[40:43], off offset:2048 sc1
	global_store_dwordx4 v[60:61], v[44:47], off offset:2048 sc1
	global_store_dwordx4 v[56:57], v[48:51], off offset:3072 sc1
	global_store_dwordx4 v[60:61], v[52:55], off offset:3072 sc1
.Lfn_loop:
	s_add_i32 s8, s9, s10
	s_cmp_lt_i32 s8, s5
	s_cbranch_scc0 .Lfn_lastB
	s_add_i32 s11, s8, s16
	s_cmp_lt_i32 s11, s5
	s_cselect_b32 s11, s11, s8
	s_lshl_b32 s12, s8, 12
	s_lshl_b32 s13, s11, 12
	v_mov_b32_e32 v82, s12
	v_mov_b32_e32 v83, 0
	v_lshl_add_u64 v[84:85], v[16:17], 0, v[82:83]
	v_lshl_add_u64 v[56:57], v[18:19], 0, v[82:83]
	v_mov_b32_e32 v82, s13
	v_lshl_add_u64 v[86:87], v[16:17], 0, v[82:83]
	v_lshl_add_u64 v[60:61], v[18:19], 0, v[82:83]
	global_load_dwordx4 v[24:27], v[84:85], off
	global_load_dwordx4 v[28:31], v[84:85], off offset:1024
	global_load_dwordx4 v[32:35], v[84:85], off offset:2048
	global_load_dwordx4 v[36:39], v[84:85], off offset:3072
	global_load_dwordx4 v[40:43], v[86:87], off
	global_load_dwordx4 v[44:47], v[86:87], off offset:1024
	global_load_dwordx4 v[48:51], v[86:87], off offset:2048
	global_load_dwordx4 v[52:55], v[86:87], off offset:3072
	s_waitcnt vmcnt(16)
	v_lshlrev_b32_e32 v21, 2, v210
	v_xor_b32_e32 v21, 0x80, v21
	v_mov_b32_e32 v23, v21
	v_mov_b32_e32 v62, v101
	v_mov_b32_e32 v63, v105
	v_mov_b32_e32 v70, v109
	v_mov_b32_e32 v71, v113
	v_mov_b32_e32 v58, v100
	v_mov_b32_e32 v59, v104
	v_mov_b32_e32 v68, v108
	v_mov_b32_e32 v69, v112
	v_pk_mul_f32 v[62:63], v[62:63], v[62:63]
	v_pk_mul_f32 v[70:71], v[70:71], v[70:71]
	v_mov_b32_e32 v64, v102
	v_mov_b32_e32 v65, v106
	v_pk_fma_f32 v[58:59], v[58:59], v[58:59], v[62:63]
	v_pk_fma_f32 v[62:63], v[68:69], v[68:69], v[70:71]
	v_mov_b32_e32 v70, v117
	v_mov_b32_e32 v71, v121
	v_mov_b32_e32 v68, v116
	v_mov_b32_e32 v69, v120
	v_mov_b32_e32 v80, v125
	v_mov_b32_e32 v81, v129
	v_pk_fma_f32 v[58:59], v[64:65], v[64:65], v[58:59]
	v_pk_mul_f32 v[64:65], v[70:71], v[70:71]
	v_mov_b32_e32 v66, v103
	v_mov_b32_e32 v67, v107
	v_mov_b32_e32 v76, v118
	v_mov_b32_e32 v77, v122
	v_mov_b32_e32 v78, v124
	v_mov_b32_e32 v79, v128
	v_pk_mul_f32 v[70:71], v[80:81], v[80:81]
	v_pk_fma_f32 v[64:65], v[68:69], v[68:69], v[64:65]
	v_mov_b32_e32 v72, v110
	v_mov_b32_e32 v73, v114
	v_mov_b32_e32 v82, v119
	v_mov_b32_e32 v83, v123
	v_mov_b32_e32 v84, v126
	v_mov_b32_e32 v85, v130
	v_pk_fma_f32 v[58:59], v[66:67], v[66:67], v[58:59]
	v_pk_fma_f32 v[66:67], v[78:79], v[78:79], v[70:71]
	v_pk_fma_f32 v[64:65], v[76:77], v[76:77], v[64:65]
	v_mov_b32_e32 v74, v111
	v_mov_b32_e32 v75, v115
	v_mov_b32_e32 v86, v127
	v_mov_b32_e32 v87, v131
	v_pk_fma_f32 v[62:63], v[72:73], v[72:73], v[62:63]
	v_pk_fma_f32 v[66:67], v[84:85], v[84:85], v[66:67]
	v_pk_fma_f32 v[64:65], v[82:83], v[82:83], v[64:65]
	v_pk_fma_f32 v[62:63], v[74:75], v[74:75], v[62:63]
	v_mov_b32_e32 v69, v58
	v_pk_fma_f32 v[66:67], v[86:87], v[86:87], v[66:67]
	v_mov_b32_e32 v68, v64
	v_mov_b32_e32 v58, v65
	v_mov_b32_e32 v71, v62
	v_mov_b32_e32 v70, v66
	v_pk_add_f32 v[58:59], v[68:69], v[58:59]
	v_mov_b32_e32 v62, v67
	v_pk_add_f32 v[58:59], v[58:59], v[70:71]
	s_nop 0
	v_pk_add_f32 v[58:59], v[58:59], v[62:63]
	ds_swizzle_b32 v63, v59 offset:swizzle(SWAP,16)
	ds_swizzle_b32 v62, v58 offset:swizzle(SWAP,16)
	s_waitcnt lgkmcnt(0)
; __device__ __forceinline__ void final_phase(const float* H, const float* g, float* out) {
;     ...
;     const float* p = H + (size_t)row * DM + lane * 4; const float* p2 = H + (size_t)row2 * DM + lane * 4; f32x4 v[4], u[4]; float ss = 0.f, ss2 = 0.f;
; #pragma unroll
;     for (int i = 0; i < 4; ++i) { v[i] = *(const f32x4*)(p + 256 * i); u[i] = *(const f32x4*)(p2 + 256 * i); }
; #pragma unroll
;     for (int i = 0; i < 4; ++i) { ss += v[i][0] * v[i][0] + v[i][1] * v[i][1] + v[i][2] * v[i][2] + v[i][3] * v[i][3]; ss2 += u[i][0] * u[i][0] + u[i][1] * u[i][1] + u[i][2] * u[i][2] + u[i][3] * u[i][3]; }
;     ss = wave_sum(ss); ss2 = wave_sum(ss2); const float rs = rsqrtf(ss * (1.0f / 1024.0f) + 1e-6f), rs2 = rsqrtf(ss2 * (1.0f / 1024.0f) + 1e-6f);
;     float* q = out + (size_t)row * DM + lane * 4; float* q2 = out + (size_t)row2 * DM + lane * 4;
; #pragma unroll
;     for (int i = 0; i < 4; ++i) { *(f32x4*)(q + 256 * i) = v[i] * rs * gv[i]; *(f32x4*)(q2 + 256 * i) = u[i] * rs2 * gv[i]; }
	v_pk_add_f32 v[58:59], v[58:59], v[62:63]
	ds_swizzle_b32 v63, v59 offset:swizzle(SWAP,8)
	ds_swizzle_b32 v62, v58 offset:swizzle(SWAP,8)
	s_waitcnt lgkmcnt(0)
	v_pk_add_f32 v[58:59], v[58:59], v[62:63]
	ds_swizzle_b32 v63, v59 offset:swizzle(SWAP,4)
	ds_swizzle_b32 v62, v58 offset:swizzle(SWAP,4)
	s_waitcnt lgkmcnt(0)
	v_pk_add_f32 v[58:59], v[58:59], v[62:63]
	ds_swizzle_b32 v63, v59 offset:swizzle(SWAP,2)
	ds_swizzle_b32 v62, v58 offset:swizzle(SWAP,2)
	s_waitcnt lgkmcnt(0)
	v_pk_add_f32 v[58:59], v[58:59], v[62:63]
	ds_swizzle_b32 v63, v59 offset:swizzle(SWAP,1)
	ds_swizzle_b32 v62, v58 offset:swizzle(SWAP,1)
	s_waitcnt lgkmcnt(0)
	v_pk_add_f32 v[58:59], v[58:59], v[62:63]
	ds_bpermute_b32 v63, v21, v59
	ds_bpermute_b32 v62, v23, v58
	s_waitcnt lgkmcnt(0)
	v_pk_add_f32 v[58:59], v[58:59], v[62:63]
	s_nop 0
	v_pk_fma_f32 v[58:59], v[58:59], s[4:5], v[20:21] op_sel_hi:[1,0,0]
	s_nop 0
	v_mul_f32_e32 v21, 0x4b800000, v59
	v_cmp_gt_f32_e64 s[0:1], s6, v59
	v_mul_f32_e32 v23, 0x4b800000, v58
	v_cmp_gt_f32_e32 vcc, s6, v58
	v_cndmask_b32_e64 v21, v59, v21, s[0:1]
	v_rsq_f32_e32 v21, v21
	v_cndmask_b32_e32 v23, v58, v23, vcc
	v_rsq_f32_e32 v23, v23
	v_mul_f32_e32 v58, 0x45800000, v21
	v_cndmask_b32_e64 v58, v21, v58, s[0:1]
	v_mul_f32_e32 v59, 0x45800000, v23
	v_cndmask_b32_e32 v62, v23, v59, vcc
	v_pk_mul_f32 v[100:101], v[100:101], v[58:59] op_sel_hi:[1,0]
	v_pk_mul_f32 v[102:103], v[102:103], v[58:59] op_sel_hi:[1,0]
	v_pk_mul_f32 v[116:117], v[116:117], v[62:63] op_sel_hi:[1,0]
	v_pk_mul_f32 v[118:119], v[118:119], v[62:63] op_sel_hi:[1,0]
	v_pk_mul_f32 v[64:65], v[104:105], v[58:59] op_sel_hi:[1,0]
	v_pk_mul_f32 v[66:67], v[106:107], v[58:59] op_sel_hi:[1,0]
	v_pk_mul_f32 v[120:121], v[120:121], v[62:63] op_sel_hi:[1,0]
	v_pk_mul_f32 v[122:123], v[122:123], v[62:63] op_sel_hi:[1,0]
	v_pk_mul_f32 v[68:69], v[108:109], v[58:59] op_sel_hi:[1,0]
	v_pk_mul_f32 v[70:71], v[110:111], v[58:59] op_sel_hi:[1,0]
	v_pk_mul_f32 v[124:125], v[124:125], v[62:63] op_sel_hi:[1,0]
	v_pk_mul_f32 v[126:127], v[126:127], v[62:63] op_sel_hi:[1,0]
	v_pk_mul_f32 v[72:73], v[112:113], v[58:59] op_sel_hi:[1,0]
	v_pk_mul_f32 v[58:59], v[114:115], v[58:59] op_sel_hi:[1,0]
	v_pk_mul_f32 v[128:129], v[128:129], v[62:63] op_sel_hi:[1,0]
	v_pk_mul_f32 v[130:131], v[130:131], v[62:63] op_sel_hi:[1,0]
	v_pk_mul_f32 v[102:103], v[2:3], v[102:103]
	v_pk_mul_f32 v[100:101], v[0:1], v[100:101]
	v_pk_mul_f32 v[106:107], v[2:3], v[118:119]
	v_pk_mul_f32 v[104:105], v[0:1], v[116:117]
	v_pk_mul_f32 v[110:111], v[6:7], v[66:67]
	v_pk_mul_f32 v[108:109], v[4:5], v[64:65]
	v_pk_mul_f32 v[114:115], v[6:7], v[122:123]
	v_pk_mul_f32 v[112:113], v[4:5], v[120:121]
	v_pk_mul_f32 v[118:119], v[10:11], v[70:71]
	v_pk_mul_f32 v[116:117], v[8:9], v[68:69]
	v_pk_mul_f32 v[122:123], v[10:11], v[126:127]
	v_pk_mul_f32 v[120:121], v[8:9], v[124:125]
	v_pk_mul_f32 v[126:127], v[14:15], v[58:59]
	v_pk_mul_f32 v[124:125], v[12:13], v[72:73]
	v_pk_mul_f32 v[130:131], v[14:15], v[130:131]
	v_pk_mul_f32 v[128:129], v[12:13], v[128:129]
	global_store_dwordx4 v[132:133], v[100:103], off sc1
	global_store_dwordx4 v[134:135], v[104:107], off sc1
	global_store_dwordx4 v[132:133], v[108:111], off offset:1024 sc1
	global_store_dwordx4 v[134:135], v[112:115], off offset:1024 sc1
	global_store_dwordx4 v[132:133], v[116:119], off offset:2048 sc1
	global_store_dwordx4 v[134:135], v[120:123], off offset:2048 sc1
	global_store_dwordx4 v[132:133], v[124:127], off offset:3072 sc1
	global_store_dwordx4 v[134:135], v[128:131], off offset:3072 sc1
	s_add_i32 s9, s8, s10
	s_cmp_lt_i32 s9, s5
	s_cbranch_scc0 .Lfn_lastA
	s_add_i32 s11, s9, s16
	s_cmp_lt_i32 s11, s5
	s_cselect_b32 s11, s11, s9
	s_lshl_b32 s12, s9, 12
	s_lshl_b32 s13, s11, 12
	v_mov_b32_e32 v82, s12
	v_mov_b32_e32 v83, 0
	v_lshl_add_u64 v[84:85], v[16:17], 0, v[82:83]
	v_lshl_add_u64 v[132:133], v[18:19], 0, v[82:83]
	v_mov_b32_e32 v82, s13
	v_lshl_add_u64 v[86:87], v[16:17], 0, v[82:83]
	v_lshl_add_u64 v[134:135], v[18:19], 0, v[82:83]
	global_load_dwordx4 v[100:103], v[84:85], off
	global_load_dwordx4 v[104:107], v[84:85], off offset:1024
	global_load_dwordx4 v[108:111], v[84:85], off offset:2048
	global_load_dwordx4 v[112:115], v[84:85], off offset:3072
	global_load_dwordx4 v[116:119], v[86:87], off
	global_load_dwordx4 v[120:123], v[86:87], off offset:1024
	global_load_dwordx4 v[124:127], v[86:87], off offset:2048
	global_load_dwordx4 v[128:131], v[86:87], off offset:3072
	s_waitcnt vmcnt(16)
	v_lshlrev_b32_e32 v21, 2, v210
	v_xor_b32_e32 v21, 0x80, v21
	v_mov_b32_e32 v23, v21
	v_mov_b32_e32 v62, v25
	v_mov_b32_e32 v63, v29
	v_mov_b32_e32 v70, v33
	v_mov_b32_e32 v71, v37
	v_mov_b32_e32 v58, v24
	v_mov_b32_e32 v59, v28
	v_mov_b32_e32 v68, v32
	v_mov_b32_e32 v69, v36
	v_pk_mul_f32 v[62:63], v[62:63], v[62:63]
	v_pk_mul_f32 v[70:71], v[70:71], v[70:71]
	v_mov_b32_e32 v64, v26
	v_mov_b32_e32 v65, v30
	v_pk_fma_f32 v[58:59], v[58:59], v[58:59], v[62:63]
	v_pk_fma_f32 v[62:63], v[68:69], v[68:69], v[70:71]
	v_mov_b32_e32 v70, v41
	v_mov_b32_e32 v71, v45
	v_mov_b32_e32 v68, v40
	v_mov_b32_e32 v69, v44
	v_mov_b32_e32 v80, v49
	v_mov_b32_e32 v81, v53
	v_pk_fma_f32 v[58:59], v[64:65], v[64:65], v[58:59]
	v_pk_mul_f32 v[64:65], v[70:71], v[70:71]
	v_mov_b32_e32 v66, v27
	v_mov_b32_e32 v67, v31
	v_mov_b32_e32 v76, v42
	v_mov_b32_e32 v77, v46
	v_mov_b32_e32 v78, v48
	v_mov_b32_e32 v79, v52
	v_pk_mul_f32 v[70:71], v[80:81], v[80:81]
	v_pk_fma_f32 v[64:65], v[68:69], v[68:69], v[64:65]
	v_mov_b32_e32 v72, v34
	v_mov_b32_e32 v73, v38
	v_mov_b32_e32 v82, v43
	v_mov_b32_e32 v83, v47
	v_mov_b32_e32 v84, v50
	v_mov_b32_e32 v85, v54
	v_pk_fma_f32 v[58:59], v[66:67], v[66:67], v[58:59]
	v_pk_fma_f32 v[66:67], v[78:79], v[78:79], v[70:71]
	v_pk_fma_f32 v[64:65], v[76:77], v[76:77], v[64:65]
	v_mov_b32_e32 v74, v35
	v_mov_b32_e32 v75, v39
	v_mov_b32_e32 v86, v51
	v_mov_b32_e32 v87, v55
	v_pk_fma_f32 v[62:63], v[72:73], v[72:73], v[62:63]
	v_pk_fma_f32 v[66:67], v[84:85], v[84:85], v[66:67]
	v_pk_fma_f32 v[64:65], v[82:83], v[82:83], v[64:65]
	v_pk_fma_f32 v[62:63], v[74:75], v[74:75], v[62:63]
	v_mov_b32_e32 v69, v58
	v_pk_fma_f32 v[66:67], v[86:87], v[86:87], v[66:67]
	v_mov_b32_e32 v68, v64
	v_mov_b32_e32 v58, v65
	v_mov_b32_e32 v71, v62
	v_mov_b32_e32 v70, v66
	v_pk_add_f32 v[58:59], v[68:69], v[58:59]
	v_mov_b32_e32 v62, v67
	v_pk_add_f32 v[58:59], v[58:59], v[70:71]
	s_nop 0
	v_pk_add_f32 v[58:59], v[58:59], v[62:63]
	ds_swizzle_b32 v63, v59 offset:swizzle(SWAP,16)
	ds_swizzle_b32 v62, v58 offset:swizzle(SWAP,16)
	s_waitcnt lgkmcnt(0)
; __device__ __forceinline__ void final_phase(const float* H, const float* g, float* out) {
;     ...
;     const float* p = H + (size_t)row * DM + lane * 4; const float* p2 = H + (size_t)row2 * DM + lane * 4; f32x4 v[4], u[4]; float ss = 0.f, ss2 = 0.f;
; #pragma unroll
;     for (int i = 0; i < 4; ++i) { v[i] = *(const f32x4*)(p + 256 * i); u[i] = *(const f32x4*)(p2 + 256 * i); }
; #pragma unroll
;     for (int i = 0; i < 4; ++i) { ss += v[i][0] * v[i][0] + v[i][1] * v[i][1] + v[i][2] * v[i][2] + v[i][3] * v[i][3]; ss2 += u[i][0] * u[i][0] + u[i][1] * u[i][1] + u[i][2] * u[i][2] + u[i][3] * u[i][3]; }
;     ss = wave_sum(ss); ss2 = wave_sum(ss2); const float rs = rsqrtf(ss * (1.0f / 1024.0f) + 1e-6f), rs2 = rsqrtf(ss2 * (1.0f / 1024.0f) + 1e-6f);
;     float* q = out + (size_t)row * DM + lane * 4; float* q2 = out + (size_t)row2 * DM + lane * 4;
; #pragma unroll
;     for (int i = 0; i < 4; ++i) { *(f32x4*)(q + 256 * i) = v[i] * rs * gv[i]; *(f32x4*)(q2 + 256 * i) = u[i] * rs2 * gv[i]; }
	v_pk_add_f32 v[58:59], v[58:59], v[62:63]
	ds_swizzle_b32 v63, v59 offset:swizzle(SWAP,8)
	ds_swizzle_b32 v62, v58 offset:swizzle(SWAP,8)
	s_waitcnt lgkmcnt(0)
	v_pk_add_f32 v[58:59], v[58:59], v[62:63]
	ds_swizzle_b32 v63, v59 offset:swizzle(SWAP,4)
	ds_swizzle_b32 v62, v58 offset:swizzle(SWAP,4)
	s_waitcnt lgkmcnt(0)
	v_pk_add_f32 v[58:59], v[58:59], v[62:63]
	ds_swizzle_b32 v63, v59 offset:swizzle(SWAP,2)
	ds_swizzle_b32 v62, v58 offset:swizzle(SWAP,2)
	s_waitcnt lgkmcnt(0)
	v_pk_add_f32 v[58:59], v[58:59], v[62:63]
	ds_swizzle_b32 v63, v59 offset:swizzle(SWAP,1)
	ds_swizzle_b32 v62, v58 offset:swizzle(SWAP,1)
	s_waitcnt lgkmcnt(0)
	v_pk_add_f32 v[58:59], v[58:59], v[62:63]
	ds_bpermute_b32 v63, v21, v59
	ds_bpermute_b32 v62, v23, v58
	s_waitcnt lgkmcnt(0)
	v_pk_add_f32 v[58:59], v[58:59], v[62:63]
	s_nop 0
	v_pk_fma_f32 v[58:59], v[58:59], s[4:5], v[20:21] op_sel_hi:[1,0,0]
	s_nop 0
	v_mul_f32_e32 v21, 0x4b800000, v59
	v_cmp_gt_f32_e64 s[0:1], s6, v59
	v_mul_f32_e32 v23, 0x4b800000, v58
	v_cmp_gt_f32_e32 vcc, s6, v58
	v_cndmask_b32_e64 v21, v59, v21, s[0:1]
	v_rsq_f32_e32 v21, v21
	v_cndmask_b32_e32 v23, v58, v23, vcc
	v_rsq_f32_e32 v23, v23
	v_mul_f32_e32 v58, 0x45800000, v21
	v_cndmask_b32_e64 v58, v21, v58, s[0:1]
	v_mul_f32_e32 v59, 0x45800000, v23
	v_cndmask_b32_e32 v62, v23, v59, vcc
	v_pk_mul_f32 v[24:25], v[24:25], v[58:59] op_sel_hi:[1,0]
	v_pk_mul_f32 v[26:27], v[26:27], v[58:59] op_sel_hi:[1,0]
	v_pk_mul_f32 v[40:41], v[40:41], v[62:63] op_sel_hi:[1,0]
	v_pk_mul_f32 v[42:43], v[42:43], v[62:63] op_sel_hi:[1,0]
	v_pk_mul_f32 v[64:65], v[28:29], v[58:59] op_sel_hi:[1,0]
	v_pk_mul_f32 v[66:67], v[30:31], v[58:59] op_sel_hi:[1,0]
	v_pk_mul_f32 v[44:45], v[44:45], v[62:63] op_sel_hi:[1,0]
	v_pk_mul_f32 v[46:47], v[46:47], v[62:63] op_sel_hi:[1,0]
	v_pk_mul_f32 v[68:69], v[32:33], v[58:59] op_sel_hi:[1,0]
	v_pk_mul_f32 v[70:71], v[34:35], v[58:59] op_sel_hi:[1,0]
	v_pk_mul_f32 v[48:49], v[48:49], v[62:63] op_sel_hi:[1,0]
	v_pk_mul_f32 v[50:51], v[50:51], v[62:63] op_sel_hi:[1,0]
	v_pk_mul_f32 v[72:73], v[36:37], v[58:59] op_sel_hi:[1,0]
	v_pk_mul_f32 v[58:59], v[38:39], v[58:59] op_sel_hi:[1,0]
	v_pk_mul_f32 v[52:53], v[52:53], v[62:63] op_sel_hi:[1,0]
	v_pk_mul_f32 v[54:55], v[54:55], v[62:63] op_sel_hi:[1,0]
	v_pk_mul_f32 v[26:27], v[2:3], v[26:27]
	v_pk_mul_f32 v[24:25], v[0:1], v[24:25]
	v_pk_mul_f32 v[30:31], v[2:3], v[42:43]
	v_pk_mul_f32 v[28:29], v[0:1], v[40:41]
	v_pk_mul_f32 v[34:35], v[6:7], v[66:67]
	v_pk_mul_f32 v[32:33], v[4:5], v[64:65]
	v_pk_mul_f32 v[38:39], v[6:7], v[46:47]
	v_pk_mul_f32 v[36:37], v[4:5], v[44:45]
	v_pk_mul_f32 v[42:43], v[10:11], v[70:71]
	v_pk_mul_f32 v[40:41], v[8:9], v[68:69]
	v_pk_mul_f32 v[46:47], v[10:11], v[50:51]
	v_pk_mul_f32 v[44:45], v[8:9], v[48:49]
	v_pk_mul_f32 v[50:51], v[14:15], v[58:59]
	v_pk_mul_f32 v[48:49], v[12:13], v[72:73]
	v_pk_mul_f32 v[54:55], v[14:15], v[54:55]
	v_pk_mul_f32 v[52:53], v[12:13], v[52:53]
	global_store_dwordx4 v[56:57], v[24:27], off sc1
	global_store_dwordx4 v[60:61], v[28:31], off sc1
	global_store_dwordx4 v[56:57], v[32:35], off offset:1024 sc1
	global_store_dwordx4 v[60:61], v[36:39], off offset:1024 sc1
	global_store_dwordx4 v[56:57], v[40:43], off offset:2048 sc1
	global_store_dwordx4 v[60:61], v[44:47], off offset:2048 sc1
	global_store_dwordx4 v[56:57], v[48:51], off offset:3072 sc1
	global_store_dwordx4 v[60:61], v[52:55], off offset:3072 sc1
	s_branch .Lfn_loop
.Lfn_lastA_first:
	s_waitcnt vmcnt(0)
	v_lshlrev_b32_e32 v21, 2, v210
	v_xor_b32_e32 v21, 0x80, v21
	v_mov_b32_e32 v23, v21
	v_mov_b32_e32 v62, v25
	v_mov_b32_e32 v63, v29
	v_mov_b32_e32 v70, v33
	v_mov_b32_e32 v71, v37
	v_mov_b32_e32 v58, v24
	v_mov_b32_e32 v59, v28
	v_mov_b32_e32 v68, v32
	v_mov_b32_e32 v69, v36
	v_pk_mul_f32 v[62:63], v[62:63], v[62:63]
	v_pk_mul_f32 v[70:71], v[70:71], v[70:71]
	v_mov_b32_e32 v64, v26
	v_mov_b32_e32 v65, v30
	v_pk_fma_f32 v[58:59], v[58:59], v[58:59], v[62:63]
	v_pk_fma_f32 v[62:63], v[68:69], v[68:69], v[70:71]
	v_mov_b32_e32 v70, v41
	v_mov_b32_e32 v71, v45
	v_mov_b32_e32 v68, v40
	v_mov_b32_e32 v69, v44
	v_mov_b32_e32 v80, v49
	v_mov_b32_e32 v81, v53
	v_pk_fma_f32 v[58:59], v[64:65], v[64:65], v[58:59]
	v_pk_mul_f32 v[64:65], v[70:71], v[70:71]
	v_mov_b32_e32 v66, v27
	v_mov_b32_e32 v67, v31
	v_mov_b32_e32 v76, v42
	v_mov_b32_e32 v77, v46
	v_mov_b32_e32 v78, v48
	v_mov_b32_e32 v79, v52
	v_pk_mul_f32 v[70:71], v[80:81], v[80:81]
	v_pk_fma_f32 v[64:65], v[68:69], v[68:69], v[64:65]
	v_mov_b32_e32 v72, v34
	v_mov_b32_e32 v73, v38
	v_mov_b32_e32 v82, v43
	v_mov_b32_e32 v83, v47
	v_mov_b32_e32 v84, v50
	v_mov_b32_e32 v85, v54
	v_pk_fma_f32 v[58:59], v[66:67], v[66:67], v[58:59]
	v_pk_fma_f32 v[66:67], v[78:79], v[78:79], v[70:71]
	v_pk_fma_f32 v[64:65], v[76:77], v[76:77], v[64:65]
	v_mov_b32_e32 v74, v35
	v_mov_b32_e32 v75, v39
	v_mov_b32_e32 v86, v51
	v_mov_b32_e32 v87, v55
	v_pk_fma_f32 v[62:63], v[72:73], v[72:73], v[62:63]
	v_pk_fma_f32 v[66:67], v[84:85], v[84:85], v[66:67]
	v_pk_fma_f32 v[64:65], v[82:83], v[82:83], v[64:65]
	v_pk_fma_f32 v[62:63], v[74:75], v[74:75], v[62:63]
	v_mov_b32_e32 v69, v58
	v_pk_fma_f32 v[66:67], v[86:87], v[86:87], v[66:67]
	v_mov_b32_e32 v68, v64
	v_mov_b32_e32 v58, v65
	v_mov_b32_e32 v71, v62
	v_mov_b32_e32 v70, v66
	v_pk_add_f32 v[58:59], v[68:69], v[58:59]
	v_mov_b32_e32 v62, v67
	v_pk_add_f32 v[58:59], v[58:59], v[70:71]
	s_nop 0
	v_pk_add_f32 v[58:59], v[58:59], v[62:63]
	ds_swizzle_b32 v63, v59 offset:swizzle(SWAP,16)
	ds_swizzle_b32 v62, v58 offset:swizzle(SWAP,16)
	s_waitcnt lgkmcnt(0)
	v_pk_add_f32 v[58:59], v[58:59], v[62:63]
	ds_swizzle_b32 v63, v59 offset:swizzle(SWAP,8)
	ds_swizzle_b32 v62, v58 offset:swizzle(SWAP,8)
	s_waitcnt lgkmcnt(0)
; __device__ __forceinline__ void final_phase(const float* H, const float* g, float* out) {
;     ...
;     const float* p = H + (size_t)row * DM + lane * 4; const float* p2 = H + (size_t)row2 * DM + lane * 4; f32x4 v[4], u[4]; float ss = 0.f, ss2 = 0.f;
; #pragma unroll
;     for (int i = 0; i < 4; ++i) { v[i] = *(const f32x4*)(p + 256 * i); u[i] = *(const f32x4*)(p2 + 256 * i); }
; #pragma unroll
;     for (int i = 0; i < 4; ++i) { ss += v[i][0] * v[i][0] + v[i][1] * v[i][1] + v[i][2] * v[i][2] + v[i][3] * v[i][3]; ss2 += u[i][0] * u[i][0] + u[i][1] * u[i][1] + u[i][2] * u[i][2] + u[i][3] * u[i][3]; }
;     ss = wave_sum(ss); ss2 = wave_sum(ss2); const float rs = rsqrtf(ss * (1.0f / 1024.0f) + 1e-6f), rs2 = rsqrtf(ss2 * (1.0f / 1024.0f) + 1e-6f);
;     float* q = out + (size_t)row * DM + lane * 4; float* q2 = out + (size_t)row2 * DM + lane * 4;
; #pragma unroll
;     for (int i = 0; i < 4; ++i) { *(f32x4*)(q + 256 * i) = v[i] * rs * gv[i]; *(f32x4*)(q2 + 256 * i) = u[i] * rs2 * gv[i]; }
	v_pk_add_f32 v[58:59], v[58:59], v[62:63]
	ds_swizzle_b32 v63, v59 offset:swizzle(SWAP,4)
	ds_swizzle_b32 v62, v58 offset:swizzle(SWAP,4)
	s_waitcnt lgkmcnt(0)
	v_pk_add_f32 v[58:59], v[58:59], v[62:63]
	ds_swizzle_b32 v63, v59 offset:swizzle(SWAP,2)
	ds_swizzle_b32 v62, v58 offset:swizzle(SWAP,2)
	s_waitcnt lgkmcnt(0)
	v_pk_add_f32 v[58:59], v[58:59], v[62:63]
	ds_swizzle_b32 v63, v59 offset:swizzle(SWAP,1)
	ds_swizzle_b32 v62, v58 offset:swizzle(SWAP,1)
	s_waitcnt lgkmcnt(0)
	v_pk_add_f32 v[58:59], v[58:59], v[62:63]
	ds_bpermute_b32 v63, v21, v59
	ds_bpermute_b32 v62, v23, v58
	s_waitcnt lgkmcnt(0)
	v_pk_add_f32 v[58:59], v[58:59], v[62:63]
	s_nop 0
	v_pk_fma_f32 v[58:59], v[58:59], s[4:5], v[20:21] op_sel_hi:[1,0,0]
	s_nop 0
	v_mul_f32_e32 v21, 0x4b800000, v59
	v_cmp_gt_f32_e64 s[0:1], s6, v59
	v_mul_f32_e32 v23, 0x4b800000, v58
	v_cmp_gt_f32_e32 vcc, s6, v58
	v_cndmask_b32_e64 v21, v59, v21, s[0:1]
	v_rsq_f32_e32 v21, v21
	v_cndmask_b32_e32 v23, v58, v23, vcc
	v_rsq_f32_e32 v23, v23
	v_mul_f32_e32 v58, 0x45800000, v21
	v_cndmask_b32_e64 v58, v21, v58, s[0:1]
	v_mul_f32_e32 v59, 0x45800000, v23
	v_cndmask_b32_e32 v62, v23, v59, vcc
	v_pk_mul_f32 v[24:25], v[24:25], v[58:59] op_sel_hi:[1,0]
	v_pk_mul_f32 v[26:27], v[26:27], v[58:59] op_sel_hi:[1,0]
	v_pk_mul_f32 v[40:41], v[40:41], v[62:63] op_sel_hi:[1,0]
	v_pk_mul_f32 v[42:43], v[42:43], v[62:63] op_sel_hi:[1,0]
	v_pk_mul_f32 v[64:65], v[28:29], v[58:59] op_sel_hi:[1,0]
	v_pk_mul_f32 v[66:67], v[30:31], v[58:59] op_sel_hi:[1,0]
	v_pk_mul_f32 v[44:45], v[44:45], v[62:63] op_sel_hi:[1,0]
	v_pk_mul_f32 v[46:47], v[46:47], v[62:63] op_sel_hi:[1,0]
	v_pk_mul_f32 v[68:69], v[32:33], v[58:59] op_sel_hi:[1,0]
	v_pk_mul_f32 v[70:71], v[34:35], v[58:59] op_sel_hi:[1,0]
	v_pk_mul_f32 v[48:49], v[48:49], v[62:63] op_sel_hi:[1,0]
	v_pk_mul_f32 v[50:51], v[50:51], v[62:63] op_sel_hi:[1,0]
	v_pk_mul_f32 v[72:73], v[36:37], v[58:59] op_sel_hi:[1,0]
	v_pk_mul_f32 v[58:59], v[38:39], v[58:59] op_sel_hi:[1,0]
	v_pk_mul_f32 v[52:53], v[52:53], v[62:63] op_sel_hi:[1,0]
	v_pk_mul_f32 v[54:55], v[54:55], v[62:63] op_sel_hi:[1,0]
	v_pk_mul_f32 v[26:27], v[2:3], v[26:27]
	v_pk_mul_f32 v[24:25], v[0:1], v[24:25]
	v_pk_mul_f32 v[30:31], v[2:3], v[42:43]
	v_pk_mul_f32 v[28:29], v[0:1], v[40:41]
	v_pk_mul_f32 v[34:35], v[6:7], v[66:67]
	v_pk_mul_f32 v[32:33], v[4:5], v[64:65]
	v_pk_mul_f32 v[38:39], v[6:7], v[46:47]
	v_pk_mul_f32 v[36:37], v[4:5], v[44:45]
	v_pk_mul_f32 v[42:43], v[10:11], v[70:71]
	v_pk_mul_f32 v[40:41], v[8:9], v[68:69]
	v_pk_mul_f32 v[46:47], v[10:11], v[50:51]
	v_pk_mul_f32 v[44:45], v[8:9], v[48:49]
	v_pk_mul_f32 v[50:51], v[14:15], v[58:59]
	v_pk_mul_f32 v[48:49], v[12:13], v[72:73]
	v_pk_mul_f32 v[54:55], v[14:15], v[54:55]
	v_pk_mul_f32 v[52:53], v[12:13], v[52:53]
	global_store_dwordx4 v[56:57], v[24:27], off sc1
	global_store_dwordx4 v[60:61], v[28:31], off sc1
	global_store_dwordx4 v[56:57], v[32:35], off offset:1024 sc1
	global_store_dwordx4 v[60:61], v[36:39], off offset:1024 sc1
	global_store_dwordx4 v[56:57], v[40:43], off offset:2048 sc1
	global_store_dwordx4 v[60:61], v[44:47], off offset:2048 sc1
	global_store_dwordx4 v[56:57], v[48:51], off offset:3072 sc1
	global_store_dwordx4 v[60:61], v[52:55], off offset:3072 sc1
	s_branch .Lfn_done
.Lfn_lastB:
	s_waitcnt vmcnt(0)
	v_lshlrev_b32_e32 v21, 2, v210
	v_xor_b32_e32 v21, 0x80, v21
	v_mov_b32_e32 v23, v21
	v_mov_b32_e32 v62, v101
	v_mov_b32_e32 v63, v105
	v_mov_b32_e32 v70, v109
	v_mov_b32_e32 v71, v113
	v_mov_b32_e32 v58, v100
	v_mov_b32_e32 v59, v104
	v_mov_b32_e32 v68, v108
	v_mov_b32_e32 v69, v112
	v_pk_mul_f32 v[62:63], v[62:63], v[62:63]
	v_pk_mul_f32 v[70:71], v[70:71], v[70:71]
	v_mov_b32_e32 v64, v102
	v_mov_b32_e32 v65, v106
	v_pk_fma_f32 v[58:59], v[58:59], v[58:59], v[62:63]
	v_pk_fma_f32 v[62:63], v[68:69], v[68:69], v[70:71]
	v_mov_b32_e32 v70, v117
	v_mov_b32_e32 v71, v121
	v_mov_b32_e32 v68, v116
	v_mov_b32_e32 v69, v120
	v_mov_b32_e32 v80, v125
	v_mov_b32_e32 v81, v129
	v_pk_fma_f32 v[58:59], v[64:65], v[64:65], v[58:59]
	v_pk_mul_f32 v[64:65], v[70:71], v[70:71]
	v_mov_b32_e32 v66, v103
	v_mov_b32_e32 v67, v107
	v_mov_b32_e32 v76, v118
	v_mov_b32_e32 v77, v122
	v_mov_b32_e32 v78, v124
	v_mov_b32_e32 v79, v128
	v_pk_mul_f32 v[70:71], v[80:81], v[80:81]
	v_pk_fma_f32 v[64:65], v[68:69], v[68:69], v[64:65]
	v_mov_b32_e32 v72, v110
	v_mov_b32_e32 v73, v114
	v_mov_b32_e32 v82, v119
	v_mov_b32_e32 v83, v123
	v_mov_b32_e32 v84, v126
	v_mov_b32_e32 v85, v130
	v_pk_fma_f32 v[58:59], v[66:67], v[66:67], v[58:59]
	v_pk_fma_f32 v[66:67], v[78:79], v[78:79], v[70:71]
	v_pk_fma_f32 v[64:65], v[76:77], v[76:77], v[64:65]
	v_mov_b32_e32 v74, v111
	v_mov_b32_e32 v75, v115
	v_mov_b32_e32 v86, v127
	v_mov_b32_e32 v87, v131
	v_pk_fma_f32 v[62:63], v[72:73], v[72:73], v[62:63]
	v_pk_fma_f32 v[66:67], v[84:85], v[84:85], v[66:67]
	v_pk_fma_f32 v[64:65], v[82:83], v[82:83], v[64:65]
	v_pk_fma_f32 v[62:63], v[74:75], v[74:75], v[62:63]
	v_mov_b32_e32 v69, v58
	v_pk_fma_f32 v[66:67], v[86:87], v[86:87], v[66:67]
	v_mov_b32_e32 v68, v64
	v_mov_b32_e32 v58, v65
	v_mov_b32_e32 v71, v62
	v_mov_b32_e32 v70, v66
	v_pk_add_f32 v[58:59], v[68:69], v[58:59]
	v_mov_b32_e32 v62, v67
	v_pk_add_f32 v[58:59], v[58:59], v[70:71]
	s_nop 0
	v_pk_add_f32 v[58:59], v[58:59], v[62:63]
	ds_swizzle_b32 v63, v59 offset:swizzle(SWAP,16)
	ds_swizzle_b32 v62, v58 offset:swizzle(SWAP,16)
	s_waitcnt lgkmcnt(0)
	v_pk_add_f32 v[58:59], v[58:59], v[62:63]
	ds_swizzle_b32 v63, v59 offset:swizzle(SWAP,8)
	ds_swizzle_b32 v62, v58 offset:swizzle(SWAP,8)
	s_waitcnt lgkmcnt(0)
	v_pk_add_f32 v[58:59], v[58:59], v[62:63]
	ds_swizzle_b32 v63, v59 offset:swizzle(SWAP,4)
	ds_swizzle_b32 v62, v58 offset:swizzle(SWAP,4)
	s_waitcnt lgkmcnt(0)
; __device__ __forceinline__ void final_phase(const float* H, const float* g, float* out) {
;     ...
;     ss = wave_sum(ss); ss2 = wave_sum(ss2); const float rs = rsqrtf(ss * (1.0f / 1024.0f) + 1e-6f), rs2 = rsqrtf(ss2 * (1.0f / 1024.0f) + 1e-6f);
;     float* q = out + (size_t)row * DM + lane * 4; float* q2 = out + (size_t)row2 * DM + lane * 4;
; #pragma unroll
;     for (int i = 0; i < 4; ++i) { *(f32x4*)(q + 256 * i) = v[i] * rs * gv[i]; *(f32x4*)(q2 + 256 * i) = u[i] * rs2 * gv[i]; }
	v_pk_add_f32 v[58:59], v[58:59], v[62:63]
	ds_swizzle_b32 v63, v59 offset:swizzle(SWAP,2)
	ds_swizzle_b32 v62, v58 offset:swizzle(SWAP,2)
	s_waitcnt lgkmcnt(0)
	v_pk_add_f32 v[58:59], v[58:59], v[62:63]
	ds_swizzle_b32 v63, v59 offset:swizzle(SWAP,1)
	ds_swizzle_b32 v62, v58 offset:swizzle(SWAP,1)
	s_waitcnt lgkmcnt(0)
	v_pk_add_f32 v[58:59], v[58:59], v[62:63]
	ds_bpermute_b32 v63, v21, v59
	ds_bpermute_b32 v62, v23, v58
	s_waitcnt lgkmcnt(0)
	v_pk_add_f32 v[58:59], v[58:59], v[62:63]
	s_nop 0
	v_pk_fma_f32 v[58:59], v[58:59], s[4:5], v[20:21] op_sel_hi:[1,0,0]
	s_nop 0
	v_mul_f32_e32 v21, 0x4b800000, v59
	v_cmp_gt_f32_e64 s[0:1], s6, v59
	v_mul_f32_e32 v23, 0x4b800000, v58
	v_cmp_gt_f32_e32 vcc, s6, v58
	v_cndmask_b32_e64 v21, v59, v21, s[0:1]
	v_rsq_f32_e32 v21, v21
	v_cndmask_b32_e32 v23, v58, v23, vcc
	v_rsq_f32_e32 v23, v23
	v_mul_f32_e32 v58, 0x45800000, v21
	v_cndmask_b32_e64 v58, v21, v58, s[0:1]
	v_mul_f32_e32 v59, 0x45800000, v23
	v_cndmask_b32_e32 v62, v23, v59, vcc
	v_pk_mul_f32 v[100:101], v[100:101], v[58:59] op_sel_hi:[1,0]
	v_pk_mul_f32 v[102:103], v[102:103], v[58:59] op_sel_hi:[1,0]
	v_pk_mul_f32 v[116:117], v[116:117], v[62:63] op_sel_hi:[1,0]
	v_pk_mul_f32 v[118:119], v[118:119], v[62:63] op_sel_hi:[1,0]
	v_pk_mul_f32 v[64:65], v[104:105], v[58:59] op_sel_hi:[1,0]
	v_pk_mul_f32 v[66:67], v[106:107], v[58:59] op_sel_hi:[1,0]
	v_pk_mul_f32 v[120:121], v[120:121], v[62:63] op_sel_hi:[1,0]
	v_pk_mul_f32 v[122:123], v[122:123], v[62:63] op_sel_hi:[1,0]
	v_pk_mul_f32 v[68:69], v[108:109], v[58:59] op_sel_hi:[1,0]
	v_pk_mul_f32 v[70:71], v[110:111], v[58:59] op_sel_hi:[1,0]
	v_pk_mul_f32 v[124:125], v[124:125], v[62:63] op_sel_hi:[1,0]
	v_pk_mul_f32 v[126:127], v[126:127], v[62:63] op_sel_hi:[1,0]
	v_pk_mul_f32 v[72:73], v[112:113], v[58:59] op_sel_hi:[1,0]
	v_pk_mul_f32 v[58:59], v[114:115], v[58:59] op_sel_hi:[1,0]
	v_pk_mul_f32 v[128:129], v[128:129], v[62:63] op_sel_hi:[1,0]
	v_pk_mul_f32 v[130:131], v[130:131], v[62:63] op_sel_hi:[1,0]
	v_pk_mul_f32 v[102:103], v[2:3], v[102:103]
	v_pk_mul_f32 v[100:101], v[0:1], v[100:101]
	v_pk_mul_f32 v[106:107], v[2:3], v[118:119]
	v_pk_mul_f32 v[104:105], v[0:1], v[116:117]
	v_pk_mul_f32 v[110:111], v[6:7], v[66:67]
	v_pk_mul_f32 v[108:109], v[4:5], v[64:65]
	v_pk_mul_f32 v[114:115], v[6:7], v[122:123]
	v_pk_mul_f32 v[112:113], v[4:5], v[120:121]
	v_pk_mul_f32 v[118:119], v[10:11], v[70:71]
	v_pk_mul_f32 v[116:117], v[8:9], v[68:69]
	v_pk_mul_f32 v[122:123], v[10:11], v[126:127]
	v_pk_mul_f32 v[120:121], v[8:9], v[124:125]
	v_pk_mul_f32 v[126:127], v[14:15], v[58:59]
	v_pk_mul_f32 v[124:125], v[12:13], v[72:73]
	v_pk_mul_f32 v[130:131], v[14:15], v[130:131]
	v_pk_mul_f32 v[128:129], v[12:13], v[128:129]
	global_store_dwordx4 v[132:133], v[100:103], off sc1
	global_store_dwordx4 v[134:135], v[104:107], off sc1
	global_store_dwordx4 v[132:133], v[108:111], off offset:1024 sc1
	global_store_dwordx4 v[134:135], v[112:115], off offset:1024 sc1
	global_store_dwordx4 v[132:133], v[116:119], off offset:2048 sc1
	global_store_dwordx4 v[134:135], v[120:123], off offset:2048 sc1
	global_store_dwordx4 v[132:133], v[124:127], off offset:3072 sc1
	global_store_dwordx4 v[134:135], v[128:131], off offset:3072 sc1
	s_branch .Lfn_done
; __device__ __forceinline__ void final_phase(const float* H, const float* g, float* out) {
;     ...
;     for (int i = 0; i < 4; ++i) { ss += v[i][0] * v[i][0] + v[i][1] * v[i][1] + v[i][2] * v[i][2] + v[i][3] * v[i][3]; ss2 += u[i][0] * u[i][0] + u[i][1] * u[i][1] + u[i][2] * u[i][2] + u[i][3] * u[i][3]; }
;     ss = wave_sum(ss); ss2 = wave_sum(ss2); const float rs = rsqrtf(ss * (1.0f / 1024.0f) + 1e-6f), rs2 = rsqrtf(ss2 * (1.0f / 1024.0f) + 1e-6f);
;     float* q = out + (size_t)row * DM + lane * 4; float* q2 = out + (size_t)row2 * DM + lane * 4;
; #pragma unroll
;     for (int i = 0; i < 4; ++i) { *(f32x4*)(q + 256 * i) = v[i] * rs * gv[i]; *(f32x4*)(q2 + 256 * i) = u[i] * rs2 * gv[i]; }
.Lfn_lastA:
	s_waitcnt vmcnt(0)
	v_lshlrev_b32_e32 v21, 2, v210
	v_xor_b32_e32 v21, 0x80, v21
	v_mov_b32_e32 v23, v21
	v_mov_b32_e32 v62, v25
	v_mov_b32_e32 v63, v29
	v_mov_b32_e32 v70, v33
	v_mov_b32_e32 v71, v37
	v_mov_b32_e32 v58, v24
	v_mov_b32_e32 v59, v28
	v_mov_b32_e32 v68, v32
	v_mov_b32_e32 v69, v36
	v_pk_mul_f32 v[62:63], v[62:63], v[62:63]
	v_pk_mul_f32 v[70:71], v[70:71], v[70:71]
	v_mov_b32_e32 v64, v26
	v_mov_b32_e32 v65, v30
	v_pk_fma_f32 v[58:59], v[58:59], v[58:59], v[62:63]
	v_pk_fma_f32 v[62:63], v[68:69], v[68:69], v[70:71]
	v_mov_b32_e32 v70, v41
	v_mov_b32_e32 v71, v45
	v_mov_b32_e32 v68, v40
	v_mov_b32_e32 v69, v44
	v_mov_b32_e32 v80, v49
	v_mov_b32_e32 v81, v53
	v_pk_fma_f32 v[58:59], v[64:65], v[64:65], v[58:59]
	v_pk_mul_f32 v[64:65], v[70:71], v[70:71]
	v_mov_b32_e32 v66, v27
	v_mov_b32_e32 v67, v31
	v_mov_b32_e32 v76, v42
	v_mov_b32_e32 v77, v46
	v_mov_b32_e32 v78, v48
	v_mov_b32_e32 v79, v52
	v_pk_mul_f32 v[70:71], v[80:81], v[80:81]
	v_pk_fma_f32 v[64:65], v[68:69], v[68:69], v[64:65]
	v_mov_b32_e32 v72, v34
	v_mov_b32_e32 v73, v38
	v_mov_b32_e32 v82, v43
	v_mov_b32_e32 v83, v47
	v_mov_b32_e32 v84, v50
	v_mov_b32_e32 v85, v54
	v_pk_fma_f32 v[58:59], v[66:67], v[66:67], v[58:59]
	v_pk_fma_f32 v[66:67], v[78:79], v[78:79], v[70:71]
	v_pk_fma_f32 v[64:65], v[76:77], v[76:77], v[64:65]
	v_mov_b32_e32 v74, v35
	v_mov_b32_e32 v75, v39
	v_mov_b32_e32 v86, v51
	v_mov_b32_e32 v87, v55
	v_pk_fma_f32 v[62:63], v[72:73], v[72:73], v[62:63]
	v_pk_fma_f32 v[66:67], v[84:85], v[84:85], v[66:67]
	v_pk_fma_f32 v[64:65], v[82:83], v[82:83], v[64:65]
	v_pk_fma_f32 v[62:63], v[74:75], v[74:75], v[62:63]
	v_mov_b32_e32 v69, v58
	v_pk_fma_f32 v[66:67], v[86:87], v[86:87], v[66:67]
	v_mov_b32_e32 v68, v64
	v_mov_b32_e32 v58, v65
	v_mov_b32_e32 v71, v62
	v_mov_b32_e32 v70, v66
	v_pk_add_f32 v[58:59], v[68:69], v[58:59]
	v_mov_b32_e32 v62, v67
	v_pk_add_f32 v[58:59], v[58:59], v[70:71]
	s_nop 0
	v_pk_add_f32 v[58:59], v[58:59], v[62:63]
	ds_swizzle_b32 v63, v59 offset:swizzle(SWAP,16)
	ds_swizzle_b32 v62, v58 offset:swizzle(SWAP,16)
	s_waitcnt lgkmcnt(0)
	v_pk_add_f32 v[58:59], v[58:59], v[62:63]
	ds_swizzle_b32 v63, v59 offset:swizzle(SWAP,8)
	ds_swizzle_b32 v62, v58 offset:swizzle(SWAP,8)
	s_waitcnt lgkmcnt(0)
	v_pk_add_f32 v[58:59], v[58:59], v[62:63]
	ds_swizzle_b32 v63, v59 offset:swizzle(SWAP,4)
	ds_swizzle_b32 v62, v58 offset:swizzle(SWAP,4)
	s_waitcnt lgkmcnt(0)
	v_pk_add_f32 v[58:59], v[58:59], v[62:63]
	ds_swizzle_b32 v63, v59 offset:swizzle(SWAP,2)
	ds_swizzle_b32 v62, v58 offset:swizzle(SWAP,2)
	s_waitcnt lgkmcnt(0)
	v_pk_add_f32 v[58:59], v[58:59], v[62:63]
	ds_swizzle_b32 v63, v59 offset:swizzle(SWAP,1)
	ds_swizzle_b32 v62, v58 offset:swizzle(SWAP,1)
	s_waitcnt lgkmcnt(0)
	v_pk_add_f32 v[58:59], v[58:59], v[62:63]
	ds_bpermute_b32 v63, v21, v59
	ds_bpermute_b32 v62, v23, v58
	s_waitcnt lgkmcnt(0)
	v_pk_add_f32 v[58:59], v[58:59], v[62:63]
	s_nop 0
	v_pk_fma_f32 v[58:59], v[58:59], s[4:5], v[20:21] op_sel_hi:[1,0,0]
	s_nop 0
	v_mul_f32_e32 v21, 0x4b800000, v59
	v_cmp_gt_f32_e64 s[0:1], s6, v59
	v_mul_f32_e32 v23, 0x4b800000, v58
	v_cmp_gt_f32_e32 vcc, s6, v58
	v_cndmask_b32_e64 v21, v59, v21, s[0:1]
	v_rsq_f32_e32 v21, v21
	v_cndmask_b32_e32 v23, v58, v23, vcc
	v_rsq_f32_e32 v23, v23
	v_mul_f32_e32 v58, 0x45800000, v21
	v_cndmask_b32_e64 v58, v21, v58, s[0:1]
	v_mul_f32_e32 v59, 0x45800000, v23
	v_cndmask_b32_e32 v62, v23, v59, vcc
	v_pk_mul_f32 v[24:25], v[24:25], v[58:59] op_sel_hi:[1,0]
	v_pk_mul_f32 v[26:27], v[26:27], v[58:59] op_sel_hi:[1,0]
	v_pk_mul_f32 v[40:41], v[40:41], v[62:63] op_sel_hi:[1,0]
	v_pk_mul_f32 v[42:43], v[42:43], v[62:63] op_sel_hi:[1,0]
	v_pk_mul_f32 v[64:65], v[28:29], v[58:59] op_sel_hi:[1,0]
	v_pk_mul_f32 v[66:67], v[30:31], v[58:59] op_sel_hi:[1,0]
	v_pk_mul_f32 v[44:45], v[44:45], v[62:63] op_sel_hi:[1,0]
	v_pk_mul_f32 v[46:47], v[46:47], v[62:63] op_sel_hi:[1,0]
	v_pk_mul_f32 v[68:69], v[32:33], v[58:59] op_sel_hi:[1,0]
	v_pk_mul_f32 v[70:71], v[34:35], v[58:59] op_sel_hi:[1,0]
	v_pk_mul_f32 v[48:49], v[48:49], v[62:63] op_sel_hi:[1,0]
	v_pk_mul_f32 v[50:51], v[50:51], v[62:63] op_sel_hi:[1,0]
	v_pk_mul_f32 v[72:73], v[36:37], v[58:59] op_sel_hi:[1,0]
	v_pk_mul_f32 v[58:59], v[38:39], v[58:59] op_sel_hi:[1,0]
	v_pk_mul_f32 v[52:53], v[52:53], v[62:63] op_sel_hi:[1,0]
	v_pk_mul_f32 v[54:55], v[54:55], v[62:63] op_sel_hi:[1,0]
	v_pk_mul_f32 v[26:27], v[2:3], v[26:27]
	v_pk_mul_f32 v[24:25], v[0:1], v[24:25]
	v_pk_mul_f32 v[30:31], v[2:3], v[42:43]
	v_pk_mul_f32 v[28:29], v[0:1], v[40:41]
	v_pk_mul_f32 v[34:35], v[6:7], v[66:67]
	v_pk_mul_f32 v[32:33], v[4:5], v[64:65]
	v_pk_mul_f32 v[38:39], v[6:7], v[46:47]
	v_pk_mul_f32 v[36:37], v[4:5], v[44:45]
	v_pk_mul_f32 v[42:43], v[10:11], v[70:71]
	v_pk_mul_f32 v[40:41], v[8:9], v[68:69]
	v_pk_mul_f32 v[46:47], v[10:11], v[50:51]
	v_pk_mul_f32 v[44:45], v[8:9], v[48:49]
	v_pk_mul_f32 v[50:51], v[14:15], v[58:59]
	v_pk_mul_f32 v[48:49], v[12:13], v[72:73]
	v_pk_mul_f32 v[54:55], v[14:15], v[54:55]
	v_pk_mul_f32 v[52:53], v[12:13], v[52:53]
	global_store_dwordx4 v[56:57], v[24:27], off sc1
	global_store_dwordx4 v[60:61], v[28:31], off sc1
	global_store_dwordx4 v[56:57], v[32:35], off offset:1024 sc1
	global_store_dwordx4 v[60:61], v[36:39], off offset:1024 sc1
	global_store_dwordx4 v[56:57], v[40:43], off offset:2048 sc1
	global_store_dwordx4 v[60:61], v[44:47], off offset:2048 sc1
	global_store_dwordx4 v[56:57], v[48:51], off offset:3072 sc1
	global_store_dwordx4 v[60:61], v[52:55], off offset:3072 sc1
